# v26 + ATTS loop: 31 redundant canonicalize v_max ops folded into v_min
# baseline (speedup 1.0000x reference)
; #define LAS __attribute__((address_space(3)))
; DI float fexp2(float x) { return __builtin_amdgcn_exp2f(x); }
; DI float frcp(float x) { return __builtin_amdgcn_rcpf(x); }
; #define MFMA32(a, b, c) __builtin_amdgcn_mfma_f32_32x32x16_bf16((a), (b), (c), 0, 0, 0)
; DI void phase_atts(ArgsP AP, LAS unsigned char* lds, int rep) {
;     ...
;             if (t <= wtmax) {
;                 const LAS char* kb_ = (const LAS char*)lds + sl * AS_ST + r32 * 144 + h * 16;
;                 f32x16 p[2];
; #pragma unroll
;                 for (int kb = 0; kb < 2; ++kb) { p[kb] = f32x16{};
; #pragma unroll
;                     for (int ks = 0; ks < 4; ++ks) { const bf16x8 a = *(const LAS bf16x8*)(kb_ + kb * 4608 + ks * 32); p[kb] = MFMA32(a, qf[ks], p[kb]); } }
;                 float T[2][4], Tp[2][4];
; #pragma unroll
;                 for (int kb = 0; kb < 2; ++kb)
; #pragma unroll
;                     for (int g = 0; g < 4; ++g) {
;                         const int key0 = t * 64 + kb * 32 + 8 * g + 4 * h;
;                         float kp[4];
; #pragma unroll
;                         for (int e = 0; e < 4; ++e) { const float z = fminf(p[kb][4 * g + e], 80.f); const bool valid = key0 + e < pos;
;                             const float ez = fexp2(z * LOG2E), kq = frcp(1.f + ez);
;                             kp[e] = valid ? kq : 1.f; p[kb][4 * g + e] = valid ? ez * kq : 0.f; }
.LBB0_70:
	s_cmp_le_i32 s62, s63
	s_cselect_b64 s[52:53], -1, 0
	s_cmp_gt_i32 s62, s63
	s_cbranch_scc1 .LBB0_72
	s_mul_i32 s2, s15, 0x2400
	v_add_u32_e32 v124, s2, v137
	ds_read_b128 v[32:35], v124
	ds_read_b128 v[36:39], v124 offset:32
	v_add_u32_e32 v177, s60, v112
	s_waitcnt lgkmcnt(1)
	v_mfma_f32_32x32x16_bf16 v[48:63], v[32:35], v[88:91], 0
	ds_read_b128 v[32:35], v124 offset:64
	ds_read_b128 v[126:129], v124 offset:96
	s_waitcnt lgkmcnt(2)
	v_mfma_f32_32x32x16_bf16 v[48:63], v[36:39], v[92:95], v[48:63]
	s_waitcnt lgkmcnt(1)
	v_mfma_f32_32x32x16_bf16 v[48:63], v[32:35], v[98:101], v[48:63]
	ds_read_b128 v[32:35], v124 offset:4608
	ds_read_b128 v[130:133], v124 offset:4640
	ds_read_b128 v[140:143], v124 offset:4672
	ds_read_b128 v[144:147], v124 offset:4704
	s_waitcnt lgkmcnt(4)
	v_mfma_f32_32x32x16_bf16 v[48:63], v[126:129], v[102:105], v[48:63]
	s_waitcnt lgkmcnt(3)
	v_mfma_f32_32x32x16_bf16 v[32:47], v[32:35], v[88:91], 0
	s_nop 9
	v_min_f32_e32 v49, 0x42a00000, v49
	v_min_f32_e32 v50, 0x42a00000, v50
	v_min_f32_e32 v51, 0x42a00000, v51
	v_mul_f32_e32 v49, 0x3fb8aa3b, v49
	v_mul_f32_e32 v50, 0x3fb8aa3b, v50
	v_mul_f32_e32 v51, 0x3fb8aa3b, v51
	v_exp_f32_e32 v129, v49
	v_exp_f32_e32 v49, v50
	s_waitcnt lgkmcnt(2)
	v_mfma_f32_32x32x16_bf16 v[32:47], v[130:133], v[92:95], v[32:47]
	v_exp_f32_e32 v50, v51
	v_min_f32_e32 v48, 0x42a00000, v48
	v_min_f32_e32 v52, 0x42a00000, v52
	v_min_f32_e32 v53, 0x42a00000, v53
	v_mul_f32_e32 v48, 0x3fb8aa3b, v48
	v_mul_f32_e32 v52, 0x3fb8aa3b, v52
	v_mul_f32_e32 v53, 0x3fb8aa3b, v53
	v_exp_f32_e32 v128, v48
	v_exp_f32_e32 v132, v52
	v_add_f32_e32 v52, 1.0, v49
	v_exp_f32_e32 v133, v53
	v_add_f32_e32 v53, 1.0, v50
	v_rcp_f32_e32 v148, v52
	v_rcp_f32_e32 v149, v53
	v_min_f32_e32 v54, 0x42a00000, v54
	v_add_f32_e32 v48, 1.0, v128
	v_add_f32_e32 v124, 1.0, v132
	v_rcp_f32_e32 v130, v48
	v_rcp_f32_e32 v48, v124
	s_waitcnt lgkmcnt(1)
	v_mfma_f32_32x32x16_bf16 v[32:47], v[140:143], v[98:101], v[32:47]
	v_mul_f32_e32 v124, v49, v148
	v_mul_f32_e32 v49, 0x3fb8aa3b, v54
	v_mul_f32_e32 v150, v50, v149
	v_exp_f32_e32 v50, v49
	v_min_f32_e32 v49, 0x42a00000, v55
	v_add_f32_e32 v51, 1.0, v129
	v_mul_f32_e32 v49, 0x3fb8aa3b, v49
	v_rcp_f32_e32 v131, v51
	v_exp_f32_e32 v51, v49
	v_add_f32_e32 v49, 1.0, v50
	s_waitcnt lgkmcnt(0)
	v_mfma_f32_32x32x16_bf16 v[32:47], v[144:147], v[102:105], v[32:47]
	v_rcp_f32_e32 v144, v49
	v_add_f32_e32 v49, 1.0, v51
	v_rcp_f32_e32 v145, v49
	v_min_f32_e32 v49, 0x42a00000, v56
	v_add_f32_e32 v126, 1.0, v133
	v_mul_f32_e32 v147, v51, v145
	v_min_f32_e32 v51, 0x42a00000, v57
	v_mul_f32_e32 v51, 0x3fb8aa3b, v51
	v_exp_f32_e32 v57, v51
	v_min_f32_e32 v51, 0x42a00000, v58
	v_mul_f32_e32 v51, 0x3fb8aa3b, v51
	v_exp_f32_e32 v52, v51
	v_min_f32_e32 v51, 0x42a00000, v59
	v_mul_f32_e32 v51, 0x3fb8aa3b, v51
	v_exp_f32_e32 v53, v51
	v_add_f32_e32 v54, 1.0, v52
	v_rcp_f32_e32 v151, v54
	v_add_f32_e32 v54, 1.0, v53
	v_rcp_f32_e32 v152, v54
	v_min_f32_e32 v54, 0x42a00000, v60
	v_mul_f32_e32 v54, 0x3fb8aa3b, v54
	v_mul_f32_e32 v153, v53, v152
	v_min_f32_e32 v53, 0x42a00000, v61
	v_mul_f32_e32 v53, 0x3fb8aa3b, v53
	v_exp_f32_e32 v59, v53
	v_min_f32_e32 v53, 0x42a00000, v62
	v_mul_f32_e32 v53, 0x3fb8aa3b, v53
	v_exp_f32_e32 v58, v54
	v_exp_f32_e32 v54, v53
	v_min_f32_e32 v53, 0x42a00000, v63
	v_mul_f32_e32 v53, 0x3fb8aa3b, v53
	v_exp_f32_e32 v55, v53
	v_min_f32_e32 v34, 0x42a00000, v34
	v_mul_f32_e32 v34, 0x3fb8aa3b, v34
	v_mul_f32_e32 v49, 0x3fb8aa3b, v49
	v_add_f32_e32 v62, 1.0, v55
	v_rcp_f32_e32 v154, v62
	v_exp_f32_e32 v62, v34
	v_min_f32_e32 v34, 0x42a00000, v35
	v_mul_f32_e32 v34, 0x3fb8aa3b, v34
	v_exp_f32_e32 v35, v34
	v_add_f32_e32 v34, 1.0, v62
	v_rcp_f32_e32 v157, v34
	v_exp_f32_e32 v56, v49
	v_add_f32_e32 v34, 1.0, v35
	v_rcp_f32_e32 v158, v34
	v_min_f32_e32 v34, 0x42a00000, v36
	v_mul_f32_e32 v34, 0x3fb8aa3b, v34
	v_exp_f32_e32 v34, v34
	v_min_f32_e32 v36, 0x42a00000, v38
	v_mul_f32_e32 v160, v35, v158
	v_add_f32_e32 v35, 1.0, v34
	v_mul_f32_e32 v36, 0x3fb8aa3b, v36
	v_rcp_f32_e32 v49, v126
	v_rcp_f32_e32 v126, v35
	v_max_f32_e32 v35, v37, v37
	v_exp_f32_e32 v37, v36
	v_min_f32_e32 v36, 0x42a00000, v39
	v_mul_f32_e32 v36, 0x3fb8aa3b, v36
	v_exp_f32_e32 v38, v36
	v_add_f32_e32 v36, 1.0, v37
	v_rcp_f32_e32 v161, v36
	v_min_f32_e32 v35, 0x42a00000, v35
	v_add_f32_e32 v36, 1.0, v38
	v_rcp_f32_e32 v162, v36
	v_mul_f32_e32 v35, 0x3fb8aa3b, v35
	v_exp_f32_e32 v35, v35
	v_mul_f32_e32 v167, v38, v162
	v_min_f32_e32 v36, 0x42a00000, v40
	v_min_f32_e32 v38, 0x42a00000, v42
	v_add_f32_e32 v39, 1.0, v35
	v_mul_f32_e32 v36, 0x3fb8aa3b, v36
	v_mul_f32_e32 v38, 0x3fb8aa3b, v38
	v_exp_f32_e32 v36, v36
	v_rcp_f32_e32 v127, v39
	v_exp_f32_e32 v39, v38
	v_min_f32_e32 v38, 0x42a00000, v43
	v_mul_f32_e32 v38, 0x3fb8aa3b, v38
	v_exp_f32_e32 v40, v38
	v_mul_f32_e32 v163, v37, v161
	v_add_f32_e32 v37, 1.0, v36
	v_rcp_f32_e32 v140, v37
	v_min_f32_e32 v37, 0x42a00000, v41
	v_add_f32_e32 v38, 1.0, v39
	v_mul_f32_e32 v37, 0x3fb8aa3b, v37
	v_rcp_f32_e32 v168, v38
	v_add_f32_e32 v38, 1.0, v40
	v_exp_f32_e32 v37, v37
	v_rcp_f32_e32 v169, v38
	v_min_f32_e32 v38, 0x42a00000, v44
	v_mul_f32_e32 v38, 0x3fb8aa3b, v38
	v_exp_f32_e32 v38, v38
	v_add_f32_e32 v41, 1.0, v37
	v_mul_f32_e32 v171, v40, v169
	v_rcp_f32_e32 v141, v41
	v_min_f32_e32 v40, 0x42a00000, v46
	v_mul_f32_e32 v40, 0x3fb8aa3b, v40
	v_min_f32_e32 v41, 0x42a00000, v47
	v_mul_f32_e32 v170, v39, v168
	v_add_f32_e32 v39, 1.0, v38
	v_exp_f32_e32 v40, v40
	v_mul_f32_e32 v41, 0x3fb8aa3b, v41
	v_rcp_f32_e32 v44, v39
	v_exp_f32_e32 v41, v41
	v_min_f32_e32 v39, 0x42a00000, v45
	v_mul_f32_e32 v39, 0x3fb8aa3b, v39
	v_exp_f32_e32 v39, v39
	v_add_f32_e32 v42, 1.0, v40
; DI float fexp2(float x) { return __builtin_amdgcn_exp2f(x); }
; DI float frcp(float x) { return __builtin_amdgcn_rcpf(x); }
; DI void phase_atts(ArgsP AP, LAS unsigned char* lds, int rep) {
;     ...
;                         for (int e = 0; e < 4; ++e) { const float z = fminf(p[kb][4 * g + e], 80.f); const bool valid = key0 + e < pos;
;                             const float ez = fexp2(z * LOG2E), kq = frcp(1.f + ez);
;                             kp[e] = valid ? kq : 1.f; p[kb][4 * g + e] = valid ? ez * kq : 0.f; }
;                         const float s2 = kp[3], s1 = s2 * kp[2], s0 = s1 * kp[1];
;                         p[kb][4 * g + 2] *= s2; p[kb][4 * g + 1] *= s1; p[kb][4 * g] *= s0;
;                         T[kb][g] = s0 * kp[0];
;                     }
; #pragma unroll
;                 for (int kb = 0; kb < 2; ++kb)
; #pragma unroll
;                     for (int g = 0; g < 4; ++g) Tp[kb][g] = __shfl_xor(T[kb][g], 32);
;                 float run = R;
; #pragma unroll
;     ...
; #pragma unroll
;                     for (int g = 3; g >= 0; --g) { const float E = run * (h == 0 ? Tp[kb][g] : 1.f); run *= T[kb][g] * Tp[kb][g];
; #pragma unroll
;                         for (int e = 0; e < 4; ++e) p[kb][4 * g + e] *= E; }
	v_rcp_f32_e32 v172, v42
	v_add_f32_e32 v42, 1.0, v41
	v_rcp_f32_e32 v173, v42
	v_add_f32_e32 v42, 1.0, v39
	v_mul_f32_e32 v146, v50, v144
	v_add_f32_e32 v50, 1.0, v56
	v_add_f32_e32 v51, 1.0, v57
	v_rcp_f32_e32 v45, v42
	v_rcp_f32_e32 v50, v50
	v_rcp_f32_e32 v51, v51
	v_mul_f32_e32 v175, v41, v173
	v_and_b32_e32 v41, 64, v224
	v_mul_f32_e32 v174, v40, v172
	v_xor_b32_e32 v40, 32, v224
	v_add_u32_e32 v41, 64, v41
	v_cmp_lt_i32_e32 vcc, v40, v41
	v_pk_mul_f32 v[142:143], v[34:35], v[126:127]
	v_add_u32_e32 v34, 1, v177
	v_cndmask_b32_e32 v40, v224, v40, vcc
	v_pk_mul_f32 v[42:43], v[38:39], v[44:45]
	v_cmp_lt_i32_e32 vcc, v177, v116
	v_cmp_lt_i32_e64 s[46:47], v34, v109
	v_pk_mul_f32 v[34:35], v[128:129], v[130:131]
	v_add_u32_e32 v39, 2, v177
	v_mul_f32_e32 v60, v52, v151
	v_add_f32_e32 v52, 1.0, v58
	v_add_f32_e32 v53, 1.0, v59
	v_lshlrev_b32_e32 v176, 2, v40
	v_pk_mul_f32 v[46:47], v[36:37], v[140:141]
	v_pk_mul_f32 v[36:37], v[56:57], v[50:51]
	v_cndmask_b32_e32 v40, 1.0, v130, vcc
	v_cndmask_b32_e32 v34, 0, v34, vcc
	v_cmp_lt_i32_e32 vcc, v39, v116
	v_add_u32_e32 v56, 3, v177
	v_rcp_f32_e32 v52, v52
	v_rcp_f32_e32 v53, v53
	v_cndmask_b32_e32 v39, 1.0, v148, vcc
	v_cndmask_b32_e32 v41, 0, v124, vcc
	v_cmp_lt_i32_e32 vcc, v56, v116
	v_cndmask_b32_e64 v38, 1.0, v131, s[46:47]
	v_cndmask_b32_e64 v35, 0, v35, s[46:47]
	v_cndmask_b32_e32 v56, 1.0, v149, vcc
	v_mul_f32_e32 v39, v56, v39
	v_mul_f32_e32 v38, v38, v39
	v_pk_mul_f32 v[134:135], v[58:59], v[52:53]
	v_pk_mul_f32 v[58:59], v[34:35], v[38:39]
	v_add_u32_e32 v34, 10, v177
	v_cndmask_b32_e32 v57, 0, v150, vcc
	v_cmp_lt_i32_e32 vcc, v34, v116
	v_add_u32_e32 v35, 11, v177
	v_add_f32_e32 v61, 1.0, v54
	v_cndmask_b32_e32 v179, 1.0, v144, vcc
	v_cndmask_b32_e32 v34, 0, v146, vcc
	v_cmp_lt_i32_e32 vcc, v35, v116
	v_rcp_f32_e32 v61, v61
	v_add_u32_e32 v35, 19, v177
	v_cndmask_b32_e32 v180, 1.0, v145, vcc
	v_mul_f32_e32 v130, v180, v34
	v_add_u32_e32 v34, 18, v177
	v_cndmask_b32_e32 v131, 0, v147, vcc
	v_cmp_lt_i32_e32 vcc, v34, v116
	v_mul_f32_e32 v178, v40, v38
	v_mul_f32_e32 v155, v54, v61
	v_cndmask_b32_e32 v181, 1.0, v151, vcc
	v_cndmask_b32_e32 v34, 0, v60, vcc
	v_cmp_lt_i32_e32 vcc, v35, v116
	v_mul_f32_e32 v56, v56, v41
	v_add_u32_e32 v35, 27, v177
	v_cndmask_b32_e32 v182, 1.0, v152, vcc
	v_mul_f32_e32 v40, v182, v34
	v_add_u32_e32 v34, 26, v177
	v_cndmask_b32_e32 v41, 0, v153, vcc
	v_cmp_lt_i32_e32 vcc, v34, v116
	v_mul_f32_e32 v156, v55, v154
	v_mul_f32_e32 v159, v62, v157
	v_cndmask_b32_e32 v152, 1.0, v61, vcc
	v_cndmask_b32_e32 v34, 0, v155, vcc
	v_cmp_lt_i32_e32 vcc, v35, v116
	v_pk_mul_f32 v[62:63], v[132:133], v[48:49]
	v_add_u32_e32 v35, 35, v177
	v_cndmask_b32_e32 v153, 1.0, v154, vcc
	v_mul_f32_e32 v132, v153, v34
	v_add_u32_e32 v34, 34, v177
	v_cndmask_b32_e32 v133, 0, v156, vcc
	v_cmp_lt_i32_e32 vcc, v34, v116
	v_add_u32_e32 v60, 58, v177
	v_add_u32_e32 v124, 59, v177
	v_cndmask_b32_e32 v154, 1.0, v157, vcc
	v_cndmask_b32_e32 v34, 0, v159, vcc
	v_cmp_lt_i32_e32 vcc, v35, v116
	v_add_u32_e32 v35, 43, v177
	v_or_b32_e32 v129, 56, v177
	v_cndmask_b32_e32 v155, 1.0, v158, vcc
	v_mul_f32_e32 v38, v155, v34
	v_add_u32_e32 v34, 42, v177
	v_cndmask_b32_e32 v39, 0, v160, vcc
	v_cmp_lt_i32_e32 vcc, v34, v116
	v_cmp_lt_i32_e64 s[48:49], v129, v116
	s_nop 0
	v_cndmask_b32_e32 v156, 1.0, v161, vcc
	v_cndmask_b32_e32 v34, 0, v163, vcc
	v_cmp_lt_i32_e32 vcc, v35, v116
	v_add_u32_e32 v35, 51, v177
	v_cmp_lt_i32_e64 s[46:47], v35, v116
	v_cndmask_b32_e32 v157, 1.0, v162, vcc
	v_mul_f32_e32 v144, v157, v34
	v_cndmask_b32_e64 v128, 1.0, v169, s[46:47]
	v_cndmask_b32_e64 v35, 0, v171, s[46:47]
	v_cmp_lt_i32_e64 s[46:47], v60, v116
	v_add_u32_e32 v34, 50, v177
	v_cndmask_b32_e32 v145, 0, v167, vcc
	v_cndmask_b32_e64 v60, 1.0, v172, s[46:47]
	v_cndmask_b32_e64 v61, 0, v174, s[46:47]
	v_cmp_lt_i32_e64 s[46:47], v124, v116
	v_cmp_lt_i32_e32 vcc, v34, v116
	v_cndmask_b32_e64 v148, 0, v42, s[48:49]
	v_cndmask_b32_e64 v124, 1.0, v173, s[46:47]
	v_mul_f32_e32 v146, v124, v61
	v_or_b32_e32 v61, 57, v177
	v_cndmask_b32_e64 v147, 0, v175, s[46:47]
	v_cmp_lt_i32_e64 s[46:47], v61, v109
	v_or_b32_e32 v42, 49, v177
	v_mul_f32_e32 v129, v124, v60
	v_cmp_lt_i32_e64 s[50:51], v42, v109
	v_cndmask_b32_e64 v61, 1.0, v45, s[46:47]
	v_cndmask_b32_e32 v60, 1.0, v168, vcc
	v_pk_mul_f32 v[60:61], v[60:61], v[128:129]
	v_cndmask_b32_e64 v45, 1.0, v44, s[48:49]
	v_cndmask_b32_e64 v44, 1.0, v141, s[50:51]
	v_pk_mul_f32 v[150:151], v[44:45], v[60:61]
	ds_bpermute_b32 v141, v176, v151
	v_or_b32_e32 v124, 48, v177
	v_cndmask_b32_e32 v34, 0, v170, vcc
	v_cmp_lt_i32_e32 vcc, v124, v116
	v_mul_f32_e32 v34, v128, v34
	v_cndmask_b32_e64 v149, 0, v43, s[46:47]
	v_cndmask_b32_e32 v42, 0, v46, vcc
	v_mov_b32_e32 v128, v61
	s_waitcnt lgkmcnt(0)
	v_cndmask_b32_e64 v46, 1.0, v141, s[42:43]
	v_or_b32_e32 v61, 41, v177
	v_cndmask_b32_e32 v140, 1.0, v140, vcc
	v_pk_mul_f32 v[44:45], v[148:149], v[128:129]
	v_mul_f32_e32 v46, v125, v46
	v_or_b32_e32 v129, 40, v177
	v_cmp_lt_i32_e64 s[46:47], v61, v109
	v_min_f32_e32 v32, 0x42a00000, v32
	v_min_f32_e32 v33, 0x42a00000, v33
	v_cndmask_b32_e64 v43, 0, v47, s[50:51]
	v_pk_mul_f32 v[44:45], v[44:45], v[46:47] op_sel_hi:[1,0]
	v_pk_mul_f32 v[46:47], v[146:147], v[46:47] op_sel_hi:[1,0]
	v_pk_mul_f32 v[140:141], v[140:141], v[150:151]
	v_cmp_lt_i32_e32 vcc, v129, v116
	v_cndmask_b32_e64 v61, 1.0, v127, s[46:47]
	v_mul_f32_e32 v147, v157, v156
	v_mul_f32_e32 v32, 0x3fb8aa3b, v32
	v_mul_f32_e32 v33, 0x3fb8aa3b, v33
	ds_bpermute_b32 v124, v176, v140
	v_cndmask_b32_e32 v126, 1.0, v126, vcc
	v_mul_f32_e32 v146, v61, v147
	v_exp_f32_e32 v32, v32
	v_exp_f32_e32 v33, v33
	v_mul_f32_e32 v148, v126, v146
	v_mov_b32_e32 v128, v150
	ds_bpermute_b32 v150, v176, v148
	v_add_f32_e32 v54, 1.0, v32
	v_add_f32_e32 v55, 1.0, v33
	s_waitcnt lgkmcnt(1)
; #define LAS __attribute__((address_space(3)))
; DI s16x4 vtr(const LAS char* p) { return __builtin_bit_cast(s16x4, __builtin_amdgcn_ds_read_tr16_b64_v4i16((LAS v4i16_t*)p)); }
; #define MFMA32(a, b, c) __builtin_amdgcn_mfma_f32_32x32x16_bf16((a), (b), (c), 0, 0, 0)
; DI bf16x8 cat8(s16x4 lo, s16x4 hi) { return __builtin_shufflevector(lo, hi, 0, 1, 2, 3, 4, 5, 6, 7); }
; DI void phase_atts(ArgsP AP, LAS unsigned char* lds, int rep) {
;     ...
;                 float run = R;
; #pragma unroll
;     ...
; #pragma unroll
;                     for (int g = 3; g >= 0; --g) { const float E = run * (h == 0 ? Tp[kb][g] : 1.f); run *= T[kb][g] * Tp[kb][g];
; #pragma unroll
;                         for (int e = 0; e < 4; ++e) p[kb][4 * g + e] *= E; }
;                 R = run;
;                 const LAS char* vb_ = (const LAS char*)lds + AS_VOFF + sl * AS_ST + (h * 4 + (i16 >> 2)) * 144 + (blk * 16 + (i16 & 3) * 4) * 2;
; #pragma unroll
;                 for (int kb = 0; kb < 2; ++kb)
; #pragma unroll
;                     for (int s = 0; s < 2; ++s) { const bf16x8 pf = pack8(p[kb], s);
; #pragma unroll
;                         for (int db = 0; db < 2; ++db) { const LAS char* vp_ = vb_ + (kb * 32 + 16 * s) * 144 + db * 64; const s16x4 lo = vtr(vp_), hi = vtr(vp_ + 8 * 144); O[db] = MFMA32(cat8(lo, hi), pf, O[db]); } }
	v_pk_mul_f32 v[126:127], v[140:141], v[124:125]
	v_rcp_f32_e32 v54, v54
	v_rcp_f32_e32 v55, v55
	v_mov_b32_e32 v149, v126
	v_mov_b32_e32 v151, v127
	v_cndmask_b32_e64 v141, 0, v143, s[46:47]
	v_cndmask_b32_e32 v140, 0, v142, vcc
	s_waitcnt lgkmcnt(0)
	v_cndmask_b32_e64 v61, 1.0, v150, s[42:43]
	v_pk_mul_f32 v[142:143], v[148:149], v[150:151]
	v_or_b32_e32 v125, 32, v177
	v_mul_f32_e32 v126, v61, v143
	v_or_b32_e32 v61, 33, v177
	v_cmp_lt_i32_e64 s[46:47], v61, v109
	v_pk_mul_f32 v[32:33], v[32:33], v[54:55]
	v_pk_mul_f32 v[140:141], v[140:141], v[146:147]
	v_cmp_lt_i32_e32 vcc, v125, v116
	v_cndmask_b32_e64 v55, 1.0, v55, s[46:47]
	v_mul_f32_e32 v147, v155, v154
	v_or_b32_e32 v61, 25, v177
	v_or_b32_e32 v125, 24, v177
	v_cndmask_b32_e32 v54, 1.0, v54, vcc
	v_cndmask_b32_e64 v33, 0, v33, s[46:47]
	v_mul_f32_e32 v146, v55, v147
	v_cmp_lt_i32_e64 s[46:47], v125, v116
	v_cmp_lt_i32_e64 s[48:49], v61, v109
	v_mul_f32_e32 v54, v54, v146
	v_cndmask_b32_e64 v125, 1.0, v52, s[46:47]
	v_cndmask_b32_e64 v52, 1.0, v53, s[48:49]
	v_mul_f32_e32 v53, v153, v152
	ds_bpermute_b32 v148, v176, v54
	v_mul_f32_e32 v52, v52, v53
	v_mov_b32_e32 v55, v142
	v_mul_f32_e32 v142, v125, v52
	ds_bpermute_b32 v150, v176, v142
	v_mov_b32_e32 v149, v143
	s_waitcnt lgkmcnt(1)
	v_pk_mul_f32 v[152:153], v[54:55], v[148:149]
	v_cndmask_b32_e64 v55, 0, v135, s[48:49]
	v_cndmask_b32_e64 v54, 0, v134, s[46:47]
	v_mov_b32_e32 v143, v152
	v_mov_b32_e32 v151, v153
	v_pk_mul_f32 v[52:53], v[54:55], v[52:53]
	s_waitcnt lgkmcnt(0)
	v_cndmask_b32_e64 v61, 1.0, v150, s[42:43]
	v_pk_mul_f32 v[54:55], v[142:143], v[150:151]
	v_pk_mul_f32 v[140:141], v[140:141], v[126:127] op_sel_hi:[1,0]
	v_pk_mul_f32 v[144:145], v[144:145], v[126:127] op_sel_hi:[1,0]
	v_mul_f32_e32 v126, v61, v55
	v_pk_mul_f32 v[134:135], v[52:53], v[126:127] op_sel_hi:[1,0]
	v_or_b32_e32 v52, 17, v177
	v_or_b32_e32 v53, 16, v177
	v_cmp_lt_i32_e64 s[48:49], v52, v109
	v_cmp_lt_i32_e64 s[46:47], v53, v116
	v_mul_f32_e32 v143, v182, v181
	v_cndmask_b32_e64 v51, 1.0, v51, s[48:49]
	v_or_b32_e32 v52, 9, v177
	v_or_b32_e32 v53, 8, v177
	v_cndmask_b32_e64 v50, 1.0, v50, s[46:47]
	v_cndmask_b32_e64 v37, 0, v37, s[48:49]
	v_mul_f32_e32 v142, v51, v143
	v_cmp_lt_i32_e64 s[48:49], v53, v116
	v_cmp_lt_i32_e64 s[50:51], v52, v109
	v_mul_f32_e32 v50, v50, v142
	v_cndmask_b32_e64 v53, 1.0, v48, s[48:49]
	v_cndmask_b32_e64 v48, 1.0, v49, s[50:51]
	v_mul_f32_e32 v49, v180, v179
	ds_bpermute_b32 v150, v176, v50
	v_mul_f32_e32 v48, v48, v49
	v_mul_f32_e32 v52, v53, v48
	v_mov_b32_e32 v51, v54
	ds_bpermute_b32 v54, v176, v52
	ds_bpermute_b32 v158, v176, v178
	v_mov_b32_e32 v151, v55
	s_waitcnt lgkmcnt(2)
	v_pk_mul_f32 v[154:155], v[50:51], v[150:151]
	v_cndmask_b32_e64 v51, 0, v63, s[50:51]
	v_cndmask_b32_e64 v50, 0, v62, s[48:49]
	v_mov_b32_e32 v53, v154
	v_mov_b32_e32 v55, v155
	v_pk_mul_f32 v[48:49], v[50:51], v[48:49]
	s_waitcnt lgkmcnt(1)
	v_cndmask_b32_e64 v61, 1.0, v54, s[42:43]
	v_pk_mul_f32 v[50:51], v[52:53], v[54:55]
	v_add_u32_e32 v125, s2, v138
	v_mul_f32_e32 v52, v61, v51
	v_pk_mul_f32 v[54:55], v[48:49], v[52:53] op_sel_hi:[1,0]
	v_mul_f32_e32 v61, v50, v51
	s_waitcnt lgkmcnt(0)
	v_cndmask_b32_e64 v48, 1.0, v158, s[42:43]
	v_pk_mul_f32 v[62:63], v[130:131], v[52:53] op_sel_hi:[1,0]
	v_mul_f32_e32 v52, v48, v61
	v_pk_mul_f32 v[58:59], v[58:59], v[52:53] op_sel_hi:[1,0]
	v_pk_mul_f32 v[56:57], v[56:57], v[52:53] op_sel_hi:[1,0]
	ds_read_b64_tr_b16 v[48:49], v125 offset:18432
	ds_read_b64_tr_b16 v[50:51], v125 offset:19584
	v_cvt_pk_bf16_f32 v52, v58, v59
	v_cvt_pk_bf16_f32 v53, v56, v57
	ds_read_b64_tr_b16 v[58:59], v125 offset:19648
	ds_read_b64_tr_b16 v[56:57], v125 offset:18496
	v_cvt_pk_bf16_f32 v54, v54, v55
	v_cvt_pk_bf16_f32 v55, v62, v63
	v_cndmask_b32_e64 v36, 0, v36, s[46:47]
	v_pk_mul_f32 v[36:37], v[36:37], v[142:143]
	s_waitcnt lgkmcnt(2)
	v_mfma_f32_32x32x16_bf16 v[0:15], v[48:51], v[52:55], v[0:15]
	v_cndmask_b32_e64 v48, 1.0, v150, s[42:43]
	v_mul_f32_e32 v62, v48, v155
	ds_read_b64_tr_b16 v[48:49], v125 offset:20736
	ds_read_b64_tr_b16 v[50:51], v125 offset:21888
	v_mul_f32_e64 v132, v132, v126
	v_mul_f32_e64 v133, v133, v126
	v_pk_mul_f32 v[36:37], v[36:37], v[62:63] op_sel_hi:[1,0]
	v_pk_mul_f32 v[40:41], v[40:41], v[62:63] op_sel_hi:[1,0]
	v_cndmask_b32_e32 v32, 0, v32, vcc
	s_waitcnt lgkmcnt(2)
	v_mfma_f32_32x32x16_bf16 v[16:31], v[56:59], v[52:55], v[16:31]
	ds_read_b64_tr_b16 v[58:59], v125 offset:21952
	ds_read_b64_tr_b16 v[56:57], v125 offset:20800
	v_cvt_pk_bf16_f32 v52, v36, v37
	v_cvt_pk_bf16_f32 v53, v40, v41
	v_cvt_pk_bf16_f32 v54, v134, v135
	v_cvt_pk_bf16_f32 v55, v132, v133
	v_cndmask_b32_e64 v36, 1.0, v148, s[42:43]
	v_pk_mul_f32 v[32:33], v[32:33], v[146:147]
	s_waitcnt lgkmcnt(2)
	v_mfma_f32_32x32x16_bf16 v[0:15], v[48:51], v[52:55], v[0:15]
	ds_read_b64_tr_b16 v[48:49], v125 offset:23040
	ds_read_b64_tr_b16 v[50:51], v125 offset:24192
	v_mul_f32_e32 v36, v36, v153
	v_mul_f32_e64 v32, v32, v36
	v_mul_f32_e64 v33, v33, v36
	v_pk_mul_f32 v[38:39], v[38:39], v[36:37] op_sel_hi:[1,0]
	v_cvt_pk_bf16_f32 v36, v32, v33
	v_cvt_pk_bf16_f32 v37, v38, v39
	v_cvt_pk_bf16_f32 v38, v140, v141
	s_waitcnt lgkmcnt(2)
	v_mfma_f32_32x32x16_bf16 v[16:31], v[56:59], v[52:55], v[16:31]
	ds_read_b64_tr_b16 v[54:55], v125 offset:24256
	ds_read_b64_tr_b16 v[52:53], v125 offset:23104
	v_cvt_pk_bf16_f32 v39, v144, v145
	v_mov_b32_e32 v129, v60
	v_cndmask_b32_e64 v40, 1.0, v124, s[42:43]
	v_pk_mul_f32 v[32:33], v[42:43], v[128:129]
	s_waitcnt lgkmcnt(2)
	v_mfma_f32_32x32x16_bf16 v[0:15], v[48:51], v[36:39], v[0:15]
	v_mul_f32_e32 v48, v40, v127
	ds_read_b64_tr_b16 v[40:41], v125 offset:25344
	ds_read_b64_tr_b16 v[42:43], v125 offset:26496
	v_mul_f32_e64 v32, v32, v48
	v_mul_f32_e64 v33, v33, v48
	v_pk_mul_f32 v[34:35], v[34:35], v[48:49] op_sel_hi:[1,0]
	v_cvt_pk_bf16_f32 v32, v32, v33
	v_cvt_pk_bf16_f32 v33, v34, v35
	v_cvt_pk_bf16_f32 v34, v44, v45
	s_waitcnt lgkmcnt(2)
	v_mfma_f32_32x32x16_bf16 v[16:31], v[52:55], v[36:39], v[16:31]
	ds_read_b64_tr_b16 v[38:39], v125 offset:26560
	ds_read_b64_tr_b16 v[36:37], v125 offset:25408
	v_cvt_pk_bf16_f32 v35, v46, v47
	s_waitcnt lgkmcnt(2)
	s_nop 0
	v_mfma_f32_32x32x16_bf16 v[0:15], v[40:43], v[32:35], v[0:15]
	v_mul_f32_e32 v40, v178, v158
	v_mul_f32_e32 v125, v40, v61
	s_waitcnt lgkmcnt(0)
	v_mfma_f32_32x32x16_bf16 v[16:31], v[36:39], v[32:35], v[16:31]
